# v43 + XCD leader does not wait for its invalidate to complete after releasing the local generation
# speedup vs baseline: 1.0089x; 1.0089x over previous
; __device__ __forceinline__ unsigned xb_ld(unsigned* p)              { return __hip_atomic_load(p, __ATOMIC_RELAXED, __HIP_MEMORY_SCOPE_AGENT); }
; __device__ __forceinline__ unsigned xb_add(unsigned* p, unsigned v) { return __hip_atomic_fetch_add(p, v, __ATOMIC_RELAXED, __HIP_MEMORY_SCOPE_AGENT); }
; #define XB_SPIN(cond, bar) do { unsigned _sp = 0; while (cond) { __builtin_amdgcn_s_sleep(1); \
;     if ((++_sp & 255u) == 0u) { if (xb_ld(&(bar)[XB_TMO])) break; if (_sp > XB_SPIN_CAP) { atomicAdd(&(bar)[XB_TMO], 1u); break; } } } } while (0)
; __device__ __forceinline__ void xcd_barrier(const XcdBarrier& b) {
;     ...
;             __builtin_amdgcn_fence(__ATOMIC_RELEASE, "agent");
;             asm volatile("s_waitcnt vmcnt(0)" ::: "memory");
;             const unsigned og = xb_add(&bar[XB_TOP], 1u);
;             const unsigned tg = og / nx;
;             if (og + 1u == (tg + 1u) * nx) xb_add(&bar[XB_TOPGEN], 1u);
;             else XB_SPIN(xb_ld(&bar[XB_TOPGEN]) == tg, bar);
;             __builtin_amdgcn_fence(__ATOMIC_ACQUIRE, "agent");
;             xb_add(&bar[XB_XGEN(b.x)], 1u);
;             asm volatile("s_waitcnt vmcnt(0)" ::: "memory");
.LBB0_14:
	s_or_b64 exec, exec, s[8:9]
	v_mov_b32_e32 v0, 0x2000
	s_waitcnt vmcnt(0)
	buffer_inv sc1
	global_atomic_add v0, v183, s[6:7] offset:1024
.LBB0_15:
	s_or_b64 exec, exec, s[4:5]
	v_readlane_b32 s2, v254, 41
	s_waitcnt lgkmcnt(0)
	s_barrier
